# P11 combine: selected experts processed two at a time (10 loads in flight), same accumulation order
# speedup vs baseline: 1.0156x; 1.0014x over previous
; DI float bf_lo(unsigned u) { return __uint_as_float(u << 16); }
; DI float bf_hi(unsigned u) { return __uint_as_float(u & 0xffff0000u); }
; DI void phase11(const Params& p) {
;     ...
;     while (mask) {
;       const int e = __ffsll((long long)mask) - 1; mask &= mask - 1ull;
;       const int slot = __shfl(myslot, e);
;       const float g = p.gate[(b * NE + e) * CAP + slot];
;       const bf16_t* y = p.Y + ((size_t)(b * NE + e) * CAP + slot) * DM + lane * 4;
; #pragma unroll
;       for (int i = 0; i < 4; ++i) {
;         const uint2 u = *(const uint2*)(y + 256 * i);
;         a[i].x += g * bf_lo(u.x); a[i].y += g * bf_hi(u.x); a[i].z += g * bf_lo(u.y); a[i].w += g * bf_hi(u.y);
;       }
;     }
.LBB0_1392:
	s_ff1_i32_b64 s14, vcc
	v_or_b32_e32 v55, s14, v51
	v_lshlrev_b32_e32 v55, 2, v55
	ds_bpermute_b32 v58, v55, v53
	v_add_u32_e32 v56, s14, v54
	v_ashrrev_i32_e32 v57, 31, v56
	v_lshlrev_b64 v[60:61], 19, v[56:57]
	s_waitcnt lgkmcnt(0)
	v_lshl_add_u64 v[60:61], s[6:7], 0, v[60:61]
	v_ashrrev_i32_e32 v59, 31, v58
	v_lshl_add_u32 v56, v56, 8, v58
	v_lshlrev_b64 v[58:59], 11, v[58:59]
	v_lshl_add_u64 v[58:59], v[60:61], 0, v[58:59]
	v_ashrrev_i32_e32 v57, 31, v56
	v_lshl_add_u64 v[58:59], v[58:59], 0, v[16:17]
	v_lshl_add_u64 v[56:57], v[56:57], 2, s[8:9]
	global_load_dwordx2 v[60:61], v[58:59], off
	global_load_dwordx2 v[62:63], v[58:59], off offset:512
	global_load_dwordx2 v[64:65], v[58:59], off offset:1024
	global_load_dwordx2 v[66:67], v[58:59], off offset:1536
	global_load_dword v68, v[56:57], off
	s_add_u32 s14, vcc_lo, -1
	s_addc_u32 s15, vcc_hi, -1
	s_and_b64 vcc, s[14:15], vcc
	s_cmp_lg_u64 vcc, 0
	s_cbranch_scc0 .Lp11_lastA
	s_ff1_i32_b64 s14, vcc
	v_or_b32_e32 v119, s14, v51
	v_lshlrev_b32_e32 v119, 2, v119
	ds_bpermute_b32 v122, v119, v53
	v_add_u32_e32 v120, s14, v54
	v_ashrrev_i32_e32 v121, 31, v120
	v_lshlrev_b64 v[124:125], 19, v[120:121]
	s_waitcnt lgkmcnt(0)
	v_lshl_add_u64 v[124:125], s[6:7], 0, v[124:125]
	v_ashrrev_i32_e32 v123, 31, v122
	v_lshl_add_u32 v120, v120, 8, v122
	v_lshlrev_b64 v[122:123], 11, v[122:123]
	v_lshl_add_u64 v[122:123], v[124:125], 0, v[122:123]
	v_ashrrev_i32_e32 v121, 31, v120
	v_lshl_add_u64 v[122:123], v[122:123], 0, v[16:17]
	v_lshl_add_u64 v[120:121], v[120:121], 2, s[8:9]
	global_load_dwordx2 v[124:125], v[122:123], off
	global_load_dwordx2 v[126:127], v[122:123], off offset:512
	global_load_dwordx2 v[128:129], v[122:123], off offset:1024
	global_load_dwordx2 v[130:131], v[122:123], off offset:1536
	global_load_dword v132, v[120:121], off
	s_add_u32 s14, vcc_lo, -1
	s_addc_u32 s15, vcc_hi, -1
	s_and_b64 vcc, s[14:15], vcc
	s_cmp_lg_u64 vcc, 0
	s_waitcnt vmcnt(9)
	v_lshlrev_b32_e32 v56, 16, v60
	v_and_b32_e32 v57, 0xffff0000, v60
	v_lshlrev_b32_e32 v58, 16, v61
	v_and_b32_e32 v59, 0xffff0000, v61
	s_waitcnt vmcnt(8)
	v_lshlrev_b32_e32 v60, 16, v62
	v_and_b32_e32 v61, 0xffff0000, v62
	v_lshlrev_b32_e32 v62, 16, v63
	v_and_b32_e32 v63, 0xffff0000, v63
	s_waitcnt vmcnt(7)
	v_lshlrev_b32_e32 v70, 16, v64
	v_and_b32_e32 v71, 0xffff0000, v64
	v_lshlrev_b32_e32 v64, 16, v65
	v_and_b32_e32 v65, 0xffff0000, v65
	s_waitcnt vmcnt(6)
	v_lshlrev_b32_e32 v72, 16, v66
	v_and_b32_e32 v73, 0xffff0000, v66
	v_lshlrev_b32_e32 v66, 16, v67
	v_and_b32_e32 v67, 0xffff0000, v67
	s_waitcnt vmcnt(5)
	v_pk_fma_f32 v[46:47], v[68:69], v[56:57], v[46:47] op_sel_hi:[0,1,1]
	v_pk_fma_f32 v[48:49], v[68:69], v[58:59], v[48:49] op_sel_hi:[0,1,1]
	v_pk_fma_f32 v[44:45], v[68:69], v[60:61], v[44:45] op_sel_hi:[0,1,1]
	v_pk_fma_f32 v[42:43], v[68:69], v[62:63], v[42:43] op_sel_hi:[0,1,1]
	v_pk_fma_f32 v[40:41], v[68:69], v[70:71], v[40:41] op_sel_hi:[0,1,1]
	v_pk_fma_f32 v[38:39], v[68:69], v[64:65], v[38:39] op_sel_hi:[0,1,1]
	v_pk_fma_f32 v[36:37], v[68:69], v[72:73], v[36:37] op_sel_hi:[0,1,1]
	v_pk_fma_f32 v[34:35], v[68:69], v[66:67], v[34:35] op_sel_hi:[0,1,1]
	s_waitcnt vmcnt(4)
	v_lshlrev_b32_e32 v120, 16, v124
	v_and_b32_e32 v121, 0xffff0000, v124
	v_lshlrev_b32_e32 v122, 16, v125
	v_and_b32_e32 v123, 0xffff0000, v125
	s_waitcnt vmcnt(3)
	v_lshlrev_b32_e32 v124, 16, v126
	v_and_b32_e32 v125, 0xffff0000, v126
	v_lshlrev_b32_e32 v126, 16, v127
	v_and_b32_e32 v127, 0xffff0000, v127
	s_waitcnt vmcnt(2)
	v_lshlrev_b32_e32 v134, 16, v128
	v_and_b32_e32 v135, 0xffff0000, v128
	v_lshlrev_b32_e32 v128, 16, v129
	v_and_b32_e32 v129, 0xffff0000, v129
	s_waitcnt vmcnt(1)
	v_lshlrev_b32_e32 v136, 16, v130
	v_and_b32_e32 v137, 0xffff0000, v130
	v_lshlrev_b32_e32 v130, 16, v131
	v_and_b32_e32 v131, 0xffff0000, v131
	s_waitcnt vmcnt(0)
	v_pk_fma_f32 v[46:47], v[132:133], v[120:121], v[46:47] op_sel_hi:[0,1,1]
	v_pk_fma_f32 v[48:49], v[132:133], v[122:123], v[48:49] op_sel_hi:[0,1,1]
	v_pk_fma_f32 v[44:45], v[132:133], v[124:125], v[44:45] op_sel_hi:[0,1,1]
	v_pk_fma_f32 v[42:43], v[132:133], v[126:127], v[42:43] op_sel_hi:[0,1,1]
	v_pk_fma_f32 v[40:41], v[132:133], v[134:135], v[40:41] op_sel_hi:[0,1,1]
	v_pk_fma_f32 v[38:39], v[132:133], v[128:129], v[38:39] op_sel_hi:[0,1,1]
	v_pk_fma_f32 v[36:37], v[132:133], v[136:137], v[36:37] op_sel_hi:[0,1,1]
	v_pk_fma_f32 v[34:35], v[132:133], v[130:131], v[34:35] op_sel_hi:[0,1,1]
	s_cmp_lg_u64 vcc, 0
	s_cbranch_scc1 .LBB0_1392
	s_branch .LBB0_1387
.Lp11_lastA:
	s_waitcnt vmcnt(4)
	v_lshlrev_b32_e32 v56, 16, v60
	v_and_b32_e32 v57, 0xffff0000, v60
	v_lshlrev_b32_e32 v58, 16, v61
	v_and_b32_e32 v59, 0xffff0000, v61
	s_waitcnt vmcnt(3)
	v_lshlrev_b32_e32 v60, 16, v62
	v_and_b32_e32 v61, 0xffff0000, v62
	v_lshlrev_b32_e32 v62, 16, v63
	v_and_b32_e32 v63, 0xffff0000, v63
	s_waitcnt vmcnt(2)
	v_lshlrev_b32_e32 v70, 16, v64
	v_and_b32_e32 v71, 0xffff0000, v64
	v_lshlrev_b32_e32 v64, 16, v65
	v_and_b32_e32 v65, 0xffff0000, v65
	s_waitcnt vmcnt(1)
	v_lshlrev_b32_e32 v72, 16, v66
	v_and_b32_e32 v73, 0xffff0000, v66
	v_lshlrev_b32_e32 v66, 16, v67
	v_and_b32_e32 v67, 0xffff0000, v67
	s_waitcnt vmcnt(0)
	v_pk_fma_f32 v[46:47], v[68:69], v[56:57], v[46:47] op_sel_hi:[0,1,1]
	v_pk_fma_f32 v[48:49], v[68:69], v[58:59], v[48:49] op_sel_hi:[0,1,1]
	v_pk_fma_f32 v[44:45], v[68:69], v[60:61], v[44:45] op_sel_hi:[0,1,1]
	v_pk_fma_f32 v[42:43], v[68:69], v[62:63], v[42:43] op_sel_hi:[0,1,1]
	v_pk_fma_f32 v[40:41], v[68:69], v[70:71], v[40:41] op_sel_hi:[0,1,1]
	v_pk_fma_f32 v[38:39], v[68:69], v[64:65], v[38:39] op_sel_hi:[0,1,1]
	v_pk_fma_f32 v[36:37], v[68:69], v[72:73], v[36:37] op_sel_hi:[0,1,1]
	v_pk_fma_f32 v[34:35], v[68:69], v[66:67], v[34:35] op_sel_hi:[0,1,1]
	s_branch .LBB0_1387
